# NSA loops: packed-f32 far-interior softmax, loop-invariant address math hoisted (selected+window), bias constant hoisted
# speedup vs baseline: 1.0261x; 1.0066x over previous
; DI void kv_load(KVRegs& r, const bf16_t* kg, const bf16_t* vg, size_t ldg, int tid) {
;   asm volatile("" : "+v"(tid));
;   const int key = tid >> 3, d8 = (tid & 7) * 8;
;   r.k = *(const u32x4*)(kg + (size_t)key * ldg + d8); r.v = *(const bf16x8*)(vg + (size_t)key * ldg + d8);
; }
; DI void kv_store(const KVRegs& r, LAS bf16_t* Ks, LAS bf16_t* Vt, int vstride, int vcol0, int tid) {
;   asm volatile("" : "+v"(tid));
;   const int key = tid >> 3, d8 = (tid & 7) * 8;
;   *(LAS u32x4*)(Ks + key * KS_STRIDE + d8) = r.k;
;   const u32x4 vd = __builtin_bit_cast(u32x4, r.v);
;   const bool odd = key & 1;
;   const unsigned s0 = odd ? vd[0] : vd[2], s1 = odd ? vd[1] : vd[3];
;   const unsigned x0 = (unsigned)__builtin_amdgcn_update_dpp(0, (int)s0, 0x128, 0xf, 0xf, false), x1 = (unsigned)__builtin_amdgcn_update_dpp(0, (int)s1, 0x128, 0xf, 0xf, false);
;   const unsigned m0 = odd ? vd[2] : vd[0], m1 = odd ? vd[3] : vd[1];
;   const unsigned lo0 = odd ? x0 : m0, hi0 = odd ? m0 : x0, lo1 = odd ? x1 : m1, hi1 = odd ? m1 : x1;
;   LAS unsigned* vp = (LAS unsigned*)(Vt + (d8 + (odd ? 4 : 0)) * vstride + vcol0 + (key & ~1));
;   const int rs = vstride >> 1;
;   vp[0] = (lo0 & 0xffffu) | (hi0 << 16); vp[rs] = (lo0 >> 16) | (hi0 & 0xffff0000u);
;   vp[2 * rs] = (lo1 & 0xffffu) | (hi1 << 16); vp[3 * rs] = (lo1 >> 16) | (hi1 & 0xffff0000u);
; }
; DI void nsa_attn_phase(int wv, const P& p_, LAS unsigned char* lds) {
;     ...
;     { const unsigned long long selm = (unsigned long long)SELM[2 * (8 * wid + tl)] | ((unsigned long long)SELM[2 * (8 * wid + tl) + 1] << 32);
;       unsigned long long rem = (unsigned long long)UNI[0] | ((unsigned long long)UNI[1] << 32);
;       m = -1e30f; l = 0.f; zero_o(O);
;       const int jw0 = qi > 8 ? qi - 8 : 0;
; #pragma unroll 1
;       while (rem) {
;         const int j = __builtin_ctzll(rem); rem &= rem - 1ull;
;         kv_store(kvr, KsB[buf], VtB[buf], 68, 0, tid);
;         __syncthreads();
;         { const bool more = rem != 0ull; const int jn = more ? __builtin_ctzll(rem) : jw0;
;           const size_t go = (size_t)(b * SEQ + jn * 64) * ld + g * 64; kv_load(kvr, hb + go + (more ? 1536 : 2048), hb + go + (more ? 1792 : 2304), ld, tid); }
;         attn_tile(KsB[buf], VtB[buf], 68, qf, O, m, l, t, tw, 8, r, h, j * 64, 1, 0x7fffffff, ((selm >> j) & 1ull) != 0ull, btl);
;         buf ^= 1;
;       }
.LBB0_773:
	s_add_i32 s0, 0, 0x22840
	v_mov_b32_e32 v0, s0
	s_waitcnt lgkmcnt(0)
	s_barrier
	ds_read_b64 v[0:1], v0
	v_ashrrev_i32_e32 v217, 3, v130
	v_lshlrev_b32_e32 v218, 3, v130
	v_and_b32_e32 v218, 56, v218
	v_mul_lo_u32 v216, v217, s90
	v_lshl_add_u32 v216, v218, 1, v216
	v_lshlrev_b32_e32 v220, 4, v130
	v_and_b32_e32 v220, 0x70, v220
	v_mul_u32_u24_e32 v221, 0x1600, v217
	v_add_u32_e32 v220, v221, v220
	v_mov_b32_e32 v221, 0
	v_and_b32_e32 v219, 8, v130
	v_lshrrev_b32_e32 v222, 1, v219
	v_or_b32_e32 v222, v218, v222
	v_mul_u32_u24_e32 v222, 0x88, v222
	v_lshlrev_b32_e32 v217, 1, v217
	v_and_b32_e32 v217, -4, v217
	v_add_u32_e32 v217, v222, v217
	v_mov_b32_e32 v218, v219
	v_add_u32_e32 v219, v134, v159
	ds_read_b32 v224, v158 offset:512
	s_max_i32 s78, s95, 8
	s_add_i32 s71, s78, -8
	s_lshl_b32 s0, s40, 1
	s_add_u32 s50, s82, s0
	s_waitcnt lgkmcnt(0)
	v_readfirstlane_b32 s60, v0
	v_cmp_eq_u64_e32 vcc, 0, v[0:1]
	v_mul_u32_u24_e32 v0, 0x44, v149
	s_mov_b32 s44, 0xf149f2ca
	v_readfirstlane_b32 s61, v1
	s_addc_u32 s57, s83, 0
	v_lshlrev_b32_e32 v164, 1, v0
	s_cbranch_vccnz .LBB0_791
	v_or_b32_e32 v0, s4, v157
	v_lshl_add_u32 v0, v0, 3, 0
	v_add_u32_e32 v0, 0x22640, v0
	ds_read_b64 v[136:137], v0
	v_mov_b32_e32 v46, v32
	v_mov_b32_e32 v47, v32
	v_mov_b32_e32 v33, v32
	v_mov_b32_e32 v34, v32
	v_mov_b32_e32 v35, v32
	v_mov_b32_e32 v36, v32
	v_mov_b32_e32 v37, v32
	v_mov_b32_e32 v38, v32
	v_mov_b32_e32 v39, v32
	v_mov_b32_e32 v40, v32
	v_mov_b32_e32 v41, v32
	v_mov_b32_e32 v42, v32
	v_mov_b32_e32 v43, v32
	v_mov_b32_e32 v44, v32
	v_mov_b32_e32 v45, v32
	v_mov_b64_e32 v[64:65], v[46:47]
	v_lshlrev_b32_e32 v144, 2, v145
	v_mov_b64_e32 v[62:63], v[44:45]
	v_mov_b64_e32 v[60:61], v[42:43]
	v_mov_b64_e32 v[58:59], v[40:41]
	v_mov_b64_e32 v[56:57], v[38:39]
	v_mov_b64_e32 v[54:55], v[36:37]
	v_mov_b64_e32 v[52:53], v[34:35]
	v_mov_b64_e32 v[50:51], v[32:33]
	v_mov_b64_e32 v[48:49], v[46:47]
	s_sub_i32 s79, s87, 63
	v_not_b32_e32 v146, v144
	v_or_b32_e32 v148, 2, v144
	v_or_b32_e32 v149, 3, v144
	v_or_b32_e32 v150, 8, v144
	v_or_b32_e32 v151, 9, v144
	v_or_b32_e32 v152, 10, v144
	v_or_b32_e32 v153, 11, v144
	v_or_b32_e32 v154, 16, v144
	v_or_b32_e32 v155, 17, v144
	v_or_b32_e32 v165, 18, v144
	v_or_b32_e32 v166, 19, v144
	v_or_b32_e32 v167, 24, v144
	v_or_b32_e32 v168, 25, v144
	v_or_b32_e32 v169, 26, v144
	v_or_b32_e32 v170, 27, v144
	s_mov_b32 s70, 0
	v_mov_b32_e32 v171, 0xf149f2ca
	v_mov_b32_e32 v143, 0
	v_mov_b64_e32 v[46:47], v[44:45]
	v_mov_b64_e32 v[44:45], v[42:43]
	v_mov_b64_e32 v[42:43], v[40:41]
	v_mov_b64_e32 v[40:41], v[38:39]
	v_mov_b64_e32 v[38:39], v[36:37]
	v_mov_b64_e32 v[36:37], v[34:35]
	v_mov_b64_e32 v[34:35], v[32:33]
.LBB0_775:
	s_add_u32 s0, s60, -1
	s_addc_u32 s1, s61, -1
	s_ff1_i32_b64 s8, s[60:61]
	s_and_b64 s[60:61], s[0:1], s[60:61]
	s_cmp_eq_u32 s70, 1
	s_cselect_b32 s0, s58, 0
	s_cselect_b32 s84, s59, s81
	v_add_u32_e32 v3, s0, v216
	v_cmp_eq_u32_e32 vcc, 0, v218
	v_mov_b32_e32 v5, v32
	v_mov_b32_e32 v7, v32
	s_waitcnt vmcnt(1)
	ds_write_b128 v3, v[126:129]
	s_waitcnt vmcnt(0)
	v_cndmask_b32_e32 v3, v122, v124, vcc
	v_cndmask_b32_e32 v4, v123, v125, vcc
	v_add_u32_e32 v0, s84, v217
	v_add_u32_e32 v12, s0, v219
	v_mov_b32_dpp v5, v3 row_ror:8 row_mask:0xf bank_mask:0xf
	v_mov_b32_dpp v7, v4 row_ror:8 row_mask:0xf bank_mask:0xf
	v_cndmask_b32_e32 v4, v5, v122, vcc
	v_cndmask_b32_e32 v5, v124, v5, vcc
	v_cndmask_b32_e32 v6, v7, v123, vcc
	v_cndmask_b32_e32 v3, v125, v7, vcc
	v_lshlrev_b32_e32 v1, 16, v5
	v_lshrrev_b32_e32 v2, 16, v4
	v_and_or_b32 v1, v4, s89, v1
	v_and_or_b32 v2, v5, s88, v2
	ds_write2_b32 v0, v1, v2 offset1:34
	v_lshlrev_b32_e32 v1, 16, v3
	v_lshrrev_b32_e32 v2, 16, v6
	v_and_or_b32 v1, v6, s89, v1
	v_and_or_b32 v2, v3, s88, v2
	ds_write2_b32 v0, v1, v2 offset0:68 offset1:102
	s_waitcnt lgkmcnt(0)
	s_barrier
	ds_read_b128 v[0:3], v12
	ds_read_b128 v[4:7], v12 offset:32
	s_waitcnt lgkmcnt(1)
	v_mfma_f32_32x32x16_bf16 v[82:97], v[0:3], v[106:109], 0
	ds_read_b128 v[0:3], v12 offset:64
	s_cmp_eq_u64 s[60:61], 0
	s_cselect_b64 s[64:65], -1, 0
	s_ff1_i32_b64 s6, s[60:61]
	s_and_b64 s[0:1], s[64:65], exec
	s_cselect_b32 s0, s71, s6
	s_movk_i32 s1, 0xc00
	s_waitcnt lgkmcnt(1)
	v_mfma_f32_32x32x16_bf16 v[82:97], v[4:7], v[110:113], v[82:97]
	ds_read_b128 v[4:7], v12 offset:96
	s_movk_i32 s6, 0x1200
	s_cselect_b32 s1, 0x1000, s1
	s_cselect_b32 s6, s6, 0xe00
	s_lshl_b32 s0, s0, 6
	s_add_i32 s0, s0, s93
	s_mul_hi_u32 s7, s0, 0x1600
	s_waitcnt lgkmcnt(1)
	v_mfma_f32_32x32x16_bf16 v[82:97], v[0:3], v[114:117], v[82:97]
	ds_read_b128 v[0:3], v12 offset:4608
	s_mulk_i32 s0, 0x1600
	s_add_u32 s9, s50, s0
	s_addc_u32 s7, s57, s7
	s_add_u32 s0, s9, s1
	s_addc_u32 s1, s7, 0
	s_add_u32 s6, s9, s6
	s_waitcnt lgkmcnt(1)
	v_mfma_f32_32x32x16_bf16 v[82:97], v[4:7], v[118:121], v[82:97]
	ds_read_b128 v[4:7], v12 offset:4640
	s_addc_u32 s7, s7, 0
	s_lshl_b32 s10, s8, 6
	s_waitcnt lgkmcnt(1)
	v_mfma_f32_32x32x16_bf16 v[66:81], v[0:3], v[106:109], 0
	v_lshl_add_u64 v[8:9], v[220:221], 0, s[0:1]
	ds_read_b128 v[0:3], v12 offset:4672
	s_waitcnt lgkmcnt(1)
	v_mfma_f32_32x32x16_bf16 v[66:81], v[4:7], v[110:113], v[66:81]
	v_lshl_add_u64 v[10:11], v[220:221], 0, s[6:7]
	ds_read_b128 v[4:7], v12 offset:4704
	global_load_dwordx4 v[126:129], v[8:9], off
	global_load_dwordx4 v[122:125], v[10:11], off
	s_waitcnt lgkmcnt(1)
	v_mfma_f32_32x32x16_bf16 v[66:81], v[0:3], v[114:117], v[66:81]
	v_lshrrev_b64 v[0:1], s8, v[136:137]
	s_sub_i32 s8, s79, s10
	s_cmpk_gt_i32 s8, 0x7f
	s_cselect_b64 s[0:1], -1, 0
	s_cmpk_lt_i32 s8, 0x80
	s_cselect_b64 s[8:9], -1, 0
	s_sub_i32 s11, s10, s87
	s_waitcnt lgkmcnt(0)
	v_mfma_f32_32x32x16_bf16 v[66:81], v[4:7], v[118:121], v[66:81]
	s_cmp_eq_u32 s11, 0x80000008
	s_cselect_b64 s[12:13], -1, 0
	v_and_b32_e32 v0, 1, v0
	s_or_b64 s[12:13], s[8:9], s[12:13]
	v_cmp_eq_u32_e64 s[6:7], 1, v0
	s_mov_b64 s[8:9], -1
	s_and_b64 vcc, exec, s[12:13]
	s_cbranch_vccz .LBB0_779
	s_and_b64 vcc, exec, s[8:9]
	s_cbranch_vccnz .LBB0_782

; DI void attn_tile(const LAS bf16_t* Ks, const LAS bf16_t* Vt, int vstride, const bf16x8 (&qf)[4], f32x16 (&O)[2], float& m, float& l,
;                   int t, int tw, int nt, int r, int h, int base, int stride, int dmax, bool ok, const LAS float* btl) {
;     ...
;   if (dmin >= 128 && dmaxw < dmax) {
;     const float cl = ok ? QK_SCALE2 : 0.f, bl = ok ? btl[128] : -1e30f;
;     float mr = -3e38f;
; #pragma unroll
;     for (int sub = 0; sub < 2; ++sub)
; #pragma unroll
;       for (int reg = 0; reg < 16; ++reg) mr = fmaxf(mr, s[sub][reg]);
;     float mx = mr * cl + bl; mx = fmaxf(mx, __shfl_xor(mx, 32));
;     mn = fmaxf(m, mx);
;     const float off = bl - mn;
; #pragma unroll
;     for (int sub = 0; sub < 2; ++sub)
; #pragma unroll
;       for (int reg = 0; reg < 16; ++reg) { const float e = __builtin_amdgcn_exp2f(s[sub][reg] * cl + off); s[sub][reg] = e; ls += e; }
;   } else {
.LBB0_779:
	v_mov_b32_e32 v0, 0xf149f2ca
	s_mov_b32 s8, 0xff61b1e6
	v_cndmask_b32_e64 v0, v0, v224, s[6:7]
	v_max3_f32 v1, v82, s8, v83
	v_max3_f32 v1, v1, v84, v85
	v_max3_f32 v1, v1, v86, v87
	v_max3_f32 v1, v1, v88, v89
	v_max3_f32 v1, v1, v90, v91
	v_max3_f32 v1, v1, v92, v93
	v_max3_f32 v1, v1, v94, v95
	v_max3_f32 v1, v1, v96, v97
	v_max3_f32 v1, v1, v66, v67
	v_max3_f32 v1, v1, v68, v69
	v_max3_f32 v1, v1, v70, v71
	v_max3_f32 v1, v1, v72, v73
	v_max3_f32 v1, v1, v74, v75
	v_max3_f32 v1, v1, v76, v77
	v_max3_f32 v1, v1, v78, v79
	v_cndmask_b32_e64 v172, 0, v242, s[6:7]
	v_max3_f32 v1, v1, v80, v81
	s_waitcnt lgkmcnt(0)
	v_fma_f32 v1, v172, v1, v0
	ds_bpermute_b32 v2, v160, v1
	s_waitcnt lgkmcnt(0)
	v_max3_f32 v139, v171, v1, v2
	v_sub_f32_e32 v174, v0, v139
	s_nop 0
	v_pk_fma_f32 v[0:1], v[82:83], v[172:173], v[174:175] op_sel_hi:[1,0,0]
	v_pk_fma_f32 v[2:3], v[84:85], v[172:173], v[174:175] op_sel_hi:[1,0,0]
	v_pk_fma_f32 v[4:5], v[86:87], v[172:173], v[174:175] op_sel_hi:[1,0,0]
	v_pk_fma_f32 v[6:7], v[88:89], v[172:173], v[174:175] op_sel_hi:[1,0,0]
	v_pk_fma_f32 v[8:9], v[90:91], v[172:173], v[174:175] op_sel_hi:[1,0,0]
	v_pk_fma_f32 v[10:11], v[92:93], v[172:173], v[174:175] op_sel_hi:[1,0,0]
	v_pk_fma_f32 v[12:13], v[94:95], v[172:173], v[174:175] op_sel_hi:[1,0,0]
	v_pk_fma_f32 v[14:15], v[96:97], v[172:173], v[174:175] op_sel_hi:[1,0,0]
	v_pk_fma_f32 v[16:17], v[66:67], v[172:173], v[174:175] op_sel_hi:[1,0,0]
	v_pk_fma_f32 v[18:19], v[68:69], v[172:173], v[174:175] op_sel_hi:[1,0,0]
	v_pk_fma_f32 v[20:21], v[70:71], v[172:173], v[174:175] op_sel_hi:[1,0,0]
	v_pk_fma_f32 v[22:23], v[72:73], v[172:173], v[174:175] op_sel_hi:[1,0,0]
	v_pk_fma_f32 v[24:25], v[74:75], v[172:173], v[174:175] op_sel_hi:[1,0,0]
	v_pk_fma_f32 v[26:27], v[76:77], v[172:173], v[174:175] op_sel_hi:[1,0,0]
	v_pk_fma_f32 v[28:29], v[78:79], v[172:173], v[174:175] op_sel_hi:[1,0,0]
	v_pk_fma_f32 v[30:31], v[80:81], v[172:173], v[174:175] op_sel_hi:[1,0,0]
	v_exp_f32_e32 v0, v0
	v_exp_f32_e32 v1, v1
	v_exp_f32_e32 v2, v2
	v_exp_f32_e32 v3, v3
	v_exp_f32_e32 v4, v4
	v_exp_f32_e32 v5, v5
	v_exp_f32_e32 v6, v6
	v_exp_f32_e32 v7, v7
	v_exp_f32_e32 v8, v8
	v_exp_f32_e32 v9, v9
	v_exp_f32_e32 v10, v10
	v_exp_f32_e32 v11, v11
	v_exp_f32_e32 v12, v12
	v_exp_f32_e32 v13, v13
	v_exp_f32_e32 v14, v14
	v_exp_f32_e32 v15, v15
	v_exp_f32_e32 v16, v16
	v_exp_f32_e32 v17, v17
	v_exp_f32_e32 v18, v18
	v_exp_f32_e32 v19, v19
	v_exp_f32_e32 v20, v20
	v_exp_f32_e32 v21, v21
	v_exp_f32_e32 v22, v22
	v_exp_f32_e32 v23, v23
	v_exp_f32_e32 v24, v24
	v_exp_f32_e32 v25, v25
	v_exp_f32_e32 v26, v26
	v_exp_f32_e32 v27, v27
	v_exp_f32_e32 v28, v28
	v_exp_f32_e32 v29, v29
	v_exp_f32_e32 v30, v30
	v_mov_b32_e32 v141, v31
	v_pk_add_f32 v[176:177], v[0:1], v[2:3]
	v_pk_add_f32 v[178:179], v[4:5], v[6:7]
	v_pk_add_f32 v[176:177], v[176:177], v[8:9]
	v_pk_add_f32 v[178:179], v[178:179], v[10:11]
	v_pk_add_f32 v[176:177], v[176:177], v[12:13]
	v_pk_add_f32 v[178:179], v[178:179], v[14:15]
	v_pk_add_f32 v[176:177], v[176:177], v[16:17]
	v_pk_add_f32 v[178:179], v[178:179], v[18:19]
	v_pk_add_f32 v[176:177], v[176:177], v[20:21]
	v_pk_add_f32 v[178:179], v[178:179], v[22:23]
	v_pk_add_f32 v[176:177], v[176:177], v[24:25]
	v_pk_add_f32 v[178:179], v[178:179], v[26:27]
	v_pk_add_f32 v[176:177], v[176:177], v[28:29]
	s_nop 0
	v_pk_add_f32 v[176:177], v[176:177], v[178:179]
	s_nop 0
	v_add_f32_e32 v140, v176, v177
	v_add_f32_e32 v140, v30, v140
	s_branch .LBB0_777

; #define LAS __attribute__((address_space(3)))
; DI void kv_load(KVRegs& r, const bf16_t* kg, const bf16_t* vg, size_t ldg, int tid) {
;   asm volatile("" : "+v"(tid));
;   const int key = tid >> 3, d8 = (tid & 7) * 8;
;   r.k = *(const u32x4*)(kg + (size_t)key * ldg + d8); r.v = *(const bf16x8*)(vg + (size_t)key * ldg + d8);
; }
; DI void kv_store(const KVRegs& r, LAS bf16_t* Ks, LAS bf16_t* Vt, int vstride, int vcol0, int tid) {
;   asm volatile("" : "+v"(tid));
;   const int key = tid >> 3, d8 = (tid & 7) * 8;
;   *(LAS u32x4*)(Ks + key * KS_STRIDE + d8) = r.k;
;   const u32x4 vd = __builtin_bit_cast(u32x4, r.v);
;   const bool odd = key & 1;
;   const unsigned s0 = odd ? vd[0] : vd[2], s1 = odd ? vd[1] : vd[3];
;   const unsigned x0 = (unsigned)__builtin_amdgcn_update_dpp(0, (int)s0, 0x128, 0xf, 0xf, false), x1 = (unsigned)__builtin_amdgcn_update_dpp(0, (int)s1, 0x128, 0xf, 0xf, false);
;   const unsigned m0 = odd ? vd[2] : vd[0], m1 = odd ? vd[3] : vd[1];
;   const unsigned lo0 = odd ? x0 : m0, hi0 = odd ? m0 : x0, lo1 = odd ? x1 : m1, hi1 = odd ? m1 : x1;
;   LAS unsigned* vp = (LAS unsigned*)(Vt + (d8 + (odd ? 4 : 0)) * vstride + vcol0 + (key & ~1));
;   const int rs = vstride >> 1;
;   vp[0] = (lo0 & 0xffffu) | (hi0 << 16); vp[rs] = (lo0 >> 16) | (hi0 & 0xffff0000u);
;   vp[2 * rs] = (lo1 & 0xffffu) | (hi1 << 16); vp[3 * rs] = (lo1 >> 16) | (hi1 & 0xffff0000u);
; }
; DI void nsa_attn_phase(int wv, const P& p_, LAS unsigned char* lds) {
;     ...
;     { m = -1e30f; l = 0.f; zero_o(O);
; #pragma unroll 1
;       for (int j = (qi > 8 ? qi - 8 : 0); j <= qi; ++j) {
;         kv_store(kvr, KsB[buf], VtB[buf], 68, 0, tid);
;         __syncthreads();
;         if (j < qi) { const size_t go = (size_t)(b * SEQ + (j + 1) * 64) * ld + g * 64; kv_load(kvr, hb + go + 2048, hb + go + 2304, ld, tid); }
;         attn_tile(KsB[buf], VtB[buf], 68, qf, O, m, l, t, tw, 8, r, h, j * 64, 1, 512, true, btl);
;         buf ^= 1;
;       }
.LBB0_794:
	s_add_i32 s17, s17, 1
	s_cmp_eq_u32 s70, 1
	s_cselect_b32 s0, s58, 0
	s_cselect_b32 s18, s59, s81
	v_add_u32_e32 v36, s0, v216
	v_cmp_eq_u32_e32 vcc, 0, v218
	v_mov_b32_e32 v38, v32
	v_mov_b32_e32 v223, v32
	s_waitcnt vmcnt(1)
	ds_write_b128 v36, v[126:129]
	s_waitcnt vmcnt(0)
	v_cndmask_b32_e32 v36, v122, v124, vcc
	v_cndmask_b32_e32 v37, v123, v125, vcc
	v_add_u32_e32 v33, s18, v217
	s_cmp_ge_i32 s17, s95
	s_cselect_b64 s[10:11], -1, 0
	v_mov_b32_dpp v38, v36 row_ror:8 row_mask:0xf bank_mask:0xf
	v_mov_b32_dpp v223, v37 row_ror:8 row_mask:0xf bank_mask:0xf
	v_cndmask_b32_e32 v37, v38, v122, vcc
	v_cndmask_b32_e32 v38, v124, v38, vcc
	v_cndmask_b32_e32 v39, v223, v123, vcc
	v_cndmask_b32_e32 v36, v125, v223, vcc
	v_lshlrev_b32_e32 v34, 16, v38
	v_lshrrev_b32_e32 v35, 16, v37
	v_and_or_b32 v34, v37, s89, v34
	v_and_or_b32 v35, v38, s88, v35
	ds_write2_b32 v33, v34, v35 offset1:34
	v_lshlrev_b32_e32 v34, 16, v36
	v_lshrrev_b32_e32 v35, 16, v39
	v_and_or_b32 v34, v39, s89, v34
	v_and_or_b32 v35, v36, s88, v35
	s_and_b64 vcc, exec, s[10:11]
	ds_write2_b32 v33, v34, v35 offset0:68 offset1:102
	s_waitcnt lgkmcnt(0)
	s_barrier
	s_cbranch_vccnz .LBB0_796
	s_mul_i32 s6, s16, 0x1600
	s_mul_hi_i32 s1, s16, 0x1600
	s_add_u32 s6, s50, s6
	s_addc_u32 s7, s57, s1
	s_add_u32 s6, s6, 0x1000
	s_addc_u32 s7, s7, 0
	v_lshl_add_u64 v[34:35], v[220:221], 0, s[6:7]
	global_load_dwordx4 v[126:129], v[34:35], off
	global_load_dwordx4 v[122:125], v[34:35], off offset:512
.LBB0_796:
	v_add_u32_e32 v33, s0, v219
	ds_read_b128 v[34:37], v33
	ds_read_b128 v[38:41], v33 offset:32
	s_cmpk_lt_i32 s15, 0x80
	s_cselect_b64 s[8:9], -1, 0
	s_cmpk_gt_i32 s15, 0x7f
	s_waitcnt lgkmcnt(1)
	v_mfma_f32_32x32x16_bf16 v[50:65], v[34:37], v[106:109], 0
	ds_read_b128 v[34:37], v33 offset:64
	ds_read_b128 v[150:153], v33 offset:4640
	s_cselect_b64 s[0:1], -1, 0
	s_cmpk_gt_i32 s14, 0xfdff
	s_cselect_b64 s[6:7], -1, 0
	s_and_b64 s[6:7], s[0:1], s[6:7]
	s_mov_b64 s[0:1], -1
	s_waitcnt lgkmcnt(2)
	v_mfma_f32_32x32x16_bf16 v[50:65], v[38:41], v[110:113], v[50:65]
	s_andn2_b64 vcc, exec, s[6:7]
	s_waitcnt lgkmcnt(1)
	v_mfma_f32_32x32x16_bf16 v[50:65], v[34:37], v[114:117], v[50:65]
	ds_read_b128 v[34:37], v33 offset:96
	s_waitcnt lgkmcnt(0)
	v_mfma_f32_32x32x16_bf16 v[50:65], v[34:37], v[118:121], v[50:65]
	ds_read_b128 v[34:37], v33 offset:4608
	s_waitcnt lgkmcnt(0)
	v_mfma_f32_32x32x16_bf16 v[34:49], v[34:37], v[106:109], 0
	v_mfma_f32_32x32x16_bf16 v[34:49], v[150:153], v[110:113], v[34:49]
	ds_read_b128 v[150:153], v33 offset:4672
	s_waitcnt lgkmcnt(0)
	v_mfma_f32_32x32x16_bf16 v[34:49], v[150:153], v[114:117], v[34:49]
	ds_read_b128 v[150:153], v33 offset:4704
	s_waitcnt lgkmcnt(0)
	v_mfma_f32_32x32x16_bf16 v[34:49], v[150:153], v[118:121], v[34:49]
	s_cbranch_vccnz .LBB0_800
	s_and_b64 vcc, exec, s[0:1]
	s_cbranch_vccnz .LBB0_805
